# gate_prep prologue: lsm fill 16 loads in flight + gamma lower-bound loads vectorized; mixer_post: row-invariant norm weights hoisted out of the row loop, gate load joined to the top batch
# baseline (speedup 1.0000x reference)
; #define p (kparams())
; __device__ __forceinline__ void gate_prep_rows(const int wv_, KPR p, int l, float* lsm  ) {
;     ...
;   { const float* gw = p->in[I_GLAGW] + (size_t)l * 2 * 16 * 256; const float* gb = p->in[I_GLAGB] + (size_t)l * 2 * 256;
;     for (int i = tid; i < 8192; i += 512) lsm[i] = gw[i];
;     lsm[8192 + tid] = gb[tid]; }
.LBB0_483:
	v_mov_b32_e32 v190, v4
	v_ashrrev_i32_e32 v191, 31, v190
	v_lshl_add_u64 v[190:191], v[190:191], 2, s[20:21]
	global_load_dword v206, v[190:191], off
	v_mov_b32_e32 v192, v5
	v_ashrrev_i32_e32 v193, 31, v192
	v_lshl_add_u64 v[192:193], v[192:193], 2, s[20:21]
	global_load_dword v207, v[192:193], off
	v_add_u32_e32 v194, 0x400, v4
	v_ashrrev_i32_e32 v195, 31, v194
	v_lshl_add_u64 v[194:195], v[194:195], 2, s[20:21]
	global_load_dword v208, v[194:195], off
	v_add_u32_e32 v196, 0x400, v5
	v_ashrrev_i32_e32 v197, 31, v196
	v_lshl_add_u64 v[196:197], v[196:197], 2, s[20:21]
	global_load_dword v209, v[196:197], off
	v_add_u32_e32 v190, 0x800, v4
	v_ashrrev_i32_e32 v191, 31, v190
	v_lshl_add_u64 v[190:191], v[190:191], 2, s[20:21]
	global_load_dword v210, v[190:191], off
	v_add_u32_e32 v192, 0x800, v5
	v_ashrrev_i32_e32 v193, 31, v192
	v_lshl_add_u64 v[192:193], v[192:193], 2, s[20:21]
	global_load_dword v211, v[192:193], off
	v_add_u32_e32 v194, 0xc00, v4
	v_ashrrev_i32_e32 v195, 31, v194
	v_lshl_add_u64 v[194:195], v[194:195], 2, s[20:21]
	global_load_dword v212, v[194:195], off
	v_add_u32_e32 v196, 0xc00, v5
	v_ashrrev_i32_e32 v197, 31, v196
	v_lshl_add_u64 v[196:197], v[196:197], 2, s[20:21]
	global_load_dword v213, v[196:197], off
	v_add_u32_e32 v190, 0x1000, v4
	v_ashrrev_i32_e32 v191, 31, v190
	v_lshl_add_u64 v[190:191], v[190:191], 2, s[20:21]
	global_load_dword v214, v[190:191], off
	v_add_u32_e32 v192, 0x1000, v5
	v_ashrrev_i32_e32 v193, 31, v192
	v_lshl_add_u64 v[192:193], v[192:193], 2, s[20:21]
	global_load_dword v215, v[192:193], off
	v_add_u32_e32 v194, 0x1400, v4
	v_ashrrev_i32_e32 v195, 31, v194
	v_lshl_add_u64 v[194:195], v[194:195], 2, s[20:21]
	global_load_dword v216, v[194:195], off
	v_add_u32_e32 v196, 0x1400, v5
	v_ashrrev_i32_e32 v197, 31, v196
	v_lshl_add_u64 v[196:197], v[196:197], 2, s[20:21]
	global_load_dword v217, v[196:197], off
	v_add_u32_e32 v190, 0x1800, v4
	v_ashrrev_i32_e32 v191, 31, v190
	v_lshl_add_u64 v[190:191], v[190:191], 2, s[20:21]
	global_load_dword v218, v[190:191], off
	v_add_u32_e32 v192, 0x1800, v5
	v_ashrrev_i32_e32 v193, 31, v192
	v_lshl_add_u64 v[192:193], v[192:193], 2, s[20:21]
	global_load_dword v219, v[192:193], off
	v_add_u32_e32 v194, 0x1c00, v4
	v_ashrrev_i32_e32 v195, 31, v194
	v_lshl_add_u64 v[194:195], v[194:195], 2, s[20:21]
	global_load_dword v220, v[194:195], off
	v_add_u32_e32 v196, 0x1c00, v5
	v_ashrrev_i32_e32 v197, 31, v196
	v_lshl_add_u64 v[196:197], v[196:197], 2, s[20:21]
	global_load_dword v221, v[196:197], off
	v_add_u32_e32 v8, -8, v8
	s_add_i32 s26, s26, 16
	v_cmp_eq_u32_e32 vcc, 0, v8
	s_or_b64 s[24:25], vcc, s[24:25]
	v_add_u32_e32 v5, 0x2000, v5
	v_add_u32_e32 v4, 0x2000, v4
	s_waitcnt vmcnt(14)
	ds_write2st64_b32 v9, v206, v207 offset1:8
	s_waitcnt vmcnt(12)
	ds_write2st64_b32 v9, v208, v209 offset0:16 offset1:24
	s_waitcnt vmcnt(10)
	ds_write2st64_b32 v9, v210, v211 offset0:32 offset1:40
	s_waitcnt vmcnt(8)
	ds_write2st64_b32 v9, v212, v213 offset0:48 offset1:56
	s_waitcnt vmcnt(6)
	ds_write2st64_b32 v9, v214, v215 offset0:64 offset1:72
	s_waitcnt vmcnt(4)
	ds_write2st64_b32 v9, v216, v217 offset0:80 offset1:88
	s_waitcnt vmcnt(2)
	ds_write2st64_b32 v9, v218, v219 offset0:96 offset1:104
	s_waitcnt vmcnt(0)
	ds_write2st64_b32 v9, v220, v221 offset0:112 offset1:120
	v_add_u32_e32 v9, 0x8000, v9
	v_mov_b32_e32 v10, s26
	s_andn2_b64 exec, exec, s[24:25]
	s_cbranch_execnz .LBB0_483
	s_or_b64 exec, exec, s[24:25]

; #define p (kparams())
; __device__ __forceinline__ void gate_prep_rows(const int wv_, KPR p, int l, float* lsm  ) {
;     ...
;   { const float* gw = p->in[I_GLAGW] + (size_t)l * 2 * 16 * 256; const float* gb = p->in[I_GLAGB] + (size_t)l * 2 * 256;
;     for (int i = tid; i < 8192; i += 512) lsm[i] = gw[i];
;     lsm[8192 + tid] = gb[tid]; }
;   float omlb[8];
;   { const float* gam = p->in[I_HGGAMMA];
; #pragma unroll
;     for (int e = 0; e < 8; ++e) { float lb = 0.f; if (l == 1) lb = __builtin_amdgcn_rcpf(1.f + __expf(gam[lane * 8 + e] - gam[C + lane * 8 + e])); omlb[e] = 1.f - lb; } }
;   __syncthreads();
;   const int d = lane >> 5, c0 = (lane & 31) * 8;
;     ...
;       const float cd = d ? cbv : ca; const float* wr_ = lsm + (d * 16 + r) * 256 + c0;
;       const f32x4 wa = *(const f32x4*)wr_, wb = *(const f32x4*)(wr_ + 4);
.LBB0_494:
	s_or_b64 exec, exec, s[14:15]
	s_waitcnt lgkmcnt(0)
	s_lshl_b64 s[4:5], s[8:9], 10
	s_add_u32 s4, s6, s4
	s_addc_u32 s5, s7, s5
	v_ashrrev_i32_e32 v1, 31, v0
	v_lshl_add_u64 v[8:9], v[0:1], 2, s[4:5]
	global_load_dword v1, v[8:9], off
	s_load_dwordx2 s[4:5], s[10:11], 0xa8
	v_and_b32_e32 v4, 63, v6
	v_readlane_b32 s6, v242, 59
	v_lshl_add_u32 v3, v0, 2, 0
	v_lshlrev_b32_e32 v140, 3, v4
	v_readlane_b32 s7, v242, 60
	s_and_b64 vcc, exec, s[6:7]
	v_mov_b32_e32 v5, 0
	s_waitcnt vmcnt(0)
	ds_write_b32 v3, v1 offset:32768
	v_mov_b32_e32 v1, 0
	v_lshlrev_b32_e32 v3, 2, v140
	v_mov_b32_e32 v7, 0
	v_mov_b32_e32 v8, 0
	v_mov_b32_e32 v9, 0
	v_mov_b32_e32 v10, 0
	v_mov_b32_e32 v11, 0
	v_mov_b32_e32 v12, 0
	s_cbranch_vccz .Lgp_lb_done
	s_waitcnt lgkmcnt(0)
	global_load_dwordx4 v[190:193], v3, s[4:5]
	global_load_dwordx4 v[194:197], v3, s[4:5] offset:16
	global_load_dwordx4 v[198:201], v3, s[4:5] offset:2048
	global_load_dwordx4 v[202:205], v3, s[4:5] offset:2064
	s_waitcnt vmcnt(0)
	v_sub_f32_e32 v5, v190, v198
	v_sub_f32_e32 v1, v191, v199
	v_sub_f32_e32 v8, v192, v200
	v_sub_f32_e32 v7, v193, v201
	v_sub_f32_e32 v10, v194, v202
	v_sub_f32_e32 v9, v195, v203
	v_sub_f32_e32 v12, v196, v204
	v_sub_f32_e32 v11, v197, v205
	v_mul_f32_e32 v5, 0x3fb8aa3b, v5
	v_mul_f32_e32 v1, 0x3fb8aa3b, v1
	v_mul_f32_e32 v8, 0x3fb8aa3b, v8
	v_mul_f32_e32 v7, 0x3fb8aa3b, v7
	v_mul_f32_e32 v10, 0x3fb8aa3b, v10
	v_mul_f32_e32 v9, 0x3fb8aa3b, v9
	v_mul_f32_e32 v12, 0x3fb8aa3b, v12
	v_mul_f32_e32 v11, 0x3fb8aa3b, v11
	v_exp_f32_e32 v5, v5
	v_exp_f32_e32 v1, v1
	v_exp_f32_e32 v8, v8
	v_exp_f32_e32 v7, v7
	v_exp_f32_e32 v10, v10
	v_exp_f32_e32 v9, v9
	v_exp_f32_e32 v12, v12
	v_exp_f32_e32 v11, v11
	v_add_f32_e32 v5, 1.0, v5
	v_add_f32_e32 v1, 1.0, v1
	v_add_f32_e32 v8, 1.0, v8
	v_add_f32_e32 v7, 1.0, v7
	v_add_f32_e32 v10, 1.0, v10
	v_add_f32_e32 v9, 1.0, v9
	v_add_f32_e32 v12, 1.0, v12
	v_add_f32_e32 v11, 1.0, v11
	v_rcp_f32_e32 v5, v5
	v_rcp_f32_e32 v1, v1
	v_rcp_f32_e32 v8, v8
	v_rcp_f32_e32 v7, v7
	v_rcp_f32_e32 v10, v10
	v_rcp_f32_e32 v9, v9
	v_rcp_f32_e32 v12, v12
	v_rcp_f32_e32 v11, v11
.Lgp_lb_done:
.LBB0_504:
	v_ashrrev_i32_e32 v0, 6, v0
	s_waitcnt lgkmcnt(0)
	v_readlane_b32 s4, v242, 2
	s_barrier
	s_nop 0
	v_add_u32_e32 v0, s4, v0
	s_movk_i32 s4, 0x4400
	v_cmp_gt_i32_e32 vcc, s4, v0
	s_and_saveexec_b64 s[8:9], vcc
	s_cbranch_execz .LBB0_507
	v_and_b32_e32 v142, 31, v6
	v_sub_f32_e32 v160, 1.0, v1
	v_sub_f32_e32 v189, 1.0, v5
	v_lshl_add_u32 v1, v142, 5, 0
	v_lshrrev_b32_e32 v5, 5, v4
	v_sub_f32_e32 v161, 1.0, v8
	v_lshl_add_u32 v8, v5, 10, v1
	v_cmp_gt_u32_e64 s[4:5], 32, v4
	v_lshl_add_u32 v1, v5, 14, v1
	v_lshlrev_b32_e32 v4, 9, v5
	v_mov_b32_e32 v5, v2
	v_sub_f32_e32 v158, 1.0, v7
	v_lshl_add_u64 v[4:5], s[12:13], 0, v[4:5]
	v_lshlrev_b32_e32 v6, 4, v142
	v_mov_b32_e32 v7, v2
	v_lshl_add_u64 v[4:5], v[4:5], 0, v[6:7]
	s_mov_b64 s[6:7], 0x390e0000
	v_sub_f32_e32 v3, 1.0, v11
	v_sub_f32_e32 v157, 1.0, v12
	v_sub_f32_e32 v156, 1.0, v9
	v_sub_f32_e32 v159, 1.0, v10
	v_lshl_add_u64 v[162:163], v[4:5], 0, s[6:7]
	ds_read_b128 v[4:7], v8 offset:32768
	ds_read_b128 v[8:11], v8 offset:32784
	ds_read_b128 v[12:15], v1
	ds_read_b128 v[16:19], v1 offset:16
	ds_read_b128 v[20:23], v1 offset:1024
	ds_read_b128 v[24:27], v1 offset:1040
	ds_read_b128 v[28:31], v1 offset:2048
	ds_read_b128 v[32:35], v1 offset:2064
	ds_read_b128 v[36:39], v1 offset:3072
	ds_read_b128 v[40:43], v1 offset:3088
	ds_read_b128 v[44:47], v1 offset:4096
	ds_read_b128 v[48:51], v1 offset:4112
	ds_read_b128 v[52:55], v1 offset:5120
	ds_read_b128 v[56:59], v1 offset:5136
	ds_read_b128 v[60:63], v1 offset:6144
	ds_read_b128 v[64:67], v1 offset:6160
	ds_read_b128 v[68:71], v1 offset:7168
	ds_read_b128 v[72:75], v1 offset:7184
	ds_read_b128 v[76:79], v1 offset:8192
	ds_read_b128 v[80:83], v1 offset:8208
	ds_read_b128 v[84:87], v1 offset:9216
	ds_read_b128 v[88:91], v1 offset:9232
	ds_read_b128 v[92:95], v1 offset:10240
	ds_read_b128 v[96:99], v1 offset:10256
	ds_read_b128 v[100:103], v1 offset:11264
	ds_read_b128 v[104:107], v1 offset:11280
	ds_read_b128 v[108:111], v1 offset:12288
	ds_read_b128 v[112:115], v1 offset:12304
	ds_read_b128 v[116:119], v1 offset:13312
	ds_read_b128 v[120:123], v1 offset:13328
	ds_read_b128 v[124:127], v1 offset:14336
	ds_read_b128 v[128:131], v1 offset:14352
	ds_read_b128 v[132:135], v1 offset:15360
	ds_read_b128 v[136:139], v1 offset:15376
	s_add_u32 s10, s12, 0xa4e0000
	s_addc_u32 s11, s13, 0
	s_mov_b64 s[12:13], 0
	v_lshlrev_b32_e32 v164, 1, v140
	v_lshlrev_b32_e32 v166, 1, v142

.LBB0_517:
	s_cmp_lt_u32 s56, 0x40001
	s_mov_b64 s[46:47], 0
	s_cselect_b64 s[58:59], -1, 0
	s_and_b64 vcc, exec, s[58:59]
	s_cbranch_vccnz .LBB0_514
	s_branch .LBB0_510
.LBB0_524:
	s_andn2_b64 vcc, exec, s[46:47]
	s_movk_i32 s35, 0x43ff
	s_movk_i32 s36, 0xffd0
	s_cbranch_vccz .LBB0_528
	s_mov_b64 s[12:13], exec
	v_mbcnt_lo_u32_b32 v17, s12, 0
	v_mbcnt_hi_u32_b32 v17, s13, v17
	v_cmp_eq_u32_e32 vcc, 0, v17
	s_and_saveexec_b64 s[10:11], vcc
	s_cbranch_execz .LBB0_527
	s_bcnt1_i32_b64 s12, s[12:13]
	v_mov_b32_e32 v17, s12
	global_atomic_add v2, v17, s[8:9]

; #define TIDX ((wv_ << 6) | lane_id_l())
; __device__ __forceinline__ float lo16(unsigned u) { return __uint_as_float(u << 16); }
; __device__ __forceinline__ float hi16(unsigned u) { return __uint_as_float(u & 0xffff0000u); }
; #define p (kparams())
; #define ws (kparams()->ws)
; __device__ __forceinline__ void mixer_post(const int wv_, KPR p, int l) {
;   const int wid = TIDX >> 6, lane = TIDX & 63, c0 = lane * 8;
;   const bf16_t* PNG = (const bf16_t*)(p->ws + WS_PNG); const bf16_t* PRE = (const bf16_t*)(p->ws + R_PRE);
;   const bf16_t* OH = (const bf16_t*)(p->ws + R_OH); const bf16_t* OG = (const bf16_t*)(p->ws + R_OG);
;   const float* RK = (const float*)(p->ws + WS_RK);
;   bf16_t* Y = (bf16_t*)(p->ws + WS_H);
;   const size_t AE = (size_t)T * 512;
;   auto ld8 = [](const bf16_t* q, float* f) { const u32x4 u = *(const u32x4*)q; f[0] = lo16(u.x); f[1] = hi16(u.x); f[2] = lo16(u.y); f[3] = hi16(u.y); f[4] = lo16(u.z); f[5] = hi16(u.z); f[6] = lo16(u.w); f[7] = hi16(u.w); };
;   auto ldh8 = [](const bf16_t* q, float* f) { const h16x8 u = *(const h16x8*)q;
; #pragma unroll
;     for (int e = 0; e < 8; ++e) f[e] = (float)u[e]; };
;   auto st8 = [](bf16_t* q, const float* f) { u32x4 o; o.x = pk2(f[0], f[1]); o.y = pk2(f[2], f[3]); o.z = pk2(f[4], f[5]); o.w = pk2(f[6], f[7]); *(u32x4*)q = o; };
;   for (int row = blockIdx.x * 8 + wid; row < T; row += gridDim.x * 8) {
;     const bf16_t* pr = PNG + (size_t)row * NNGP;
;     {
;       float a[8], bq[8], v[8], g[8], y[8];
;       ld8(pr + c0, a); ld8(pr + 512 + c0, bq); ldh8(PRE + AE + (size_t)row * 512 + c0, v); ldh8(PRE + 9 * AE + (size_t)row * 512 + c0, g);
;       float sm = 0.f;
; #pragma unroll
;       for (int e = 0; e < 8; ++e) { y[e] = a[e] + bq[e]; sm += y[e]; }
;       const float mean = group_sum(sm, 8) * (1.f / 64.f);
;       float sq = 0.f;
; #pragma unroll
;       for (int e = 0; e < 8; ++e) { y[e] -= mean; sq += y[e] * y[e]; }
;       const float rstd = rsqrtf(group_sum(sq, 8) * (1.f / 64.f) + 64e-5f);
;       const float rk = RK[(size_t)row * 8 + (lane >> 3)];
; #pragma unroll
;       for (int e = 0; e < 8; ++e) { const int c = c0 + e; y[e] = (y[e] * rstd * p->in[I_RWLNW][l * C + c] + p->in[I_RWLNB][l * C + c] + rk * v[e]) * g[e]; }
;       st8(Y + (size_t)row * 512 + c0, y); }
.LBB0_741:
	s_or_b64 exec, exec, s[4:5]
	s_mov_b64 s[6:7], s[0:1]
	s_waitcnt lgkmcnt(0)
	v_mov_b32_e32 v0, v153
	s_barrier
	v_readlane_b32 s4, v242, 2
	v_or_b32_e32 v0, s77, v0
	v_ashrrev_i32_e32 v0, 6, v0
	v_add_u32_e32 v0, s4, v0
	s_movk_i32 s4, 0x4400
	v_mov_b32_e32 v1, v153
	v_cmp_gt_i32_e32 vcc, s4, v0
	s_and_saveexec_b64 s[4:5], vcc
	s_cbranch_execz .LBB0_744
	s_load_dwordx2 s[8:9], s[6:7], 0x118
	s_load_dwordx2 s[12:13], s[6:7], 0xc8
	v_and_b32_e32 v3, 63, v1
	s_waitcnt vmcnt(2)
	v_mov_b32_e32 v5, v2
	v_lshlrev_b32_e32 v4, 4, v3
	v_lshrrev_b32_e32 v1, 1, v1
	s_waitcnt lgkmcnt(0)
	v_lshl_add_u64 v[4:5], s[8:9], 0, v[4:5]
	s_mov_b64 s[10:11], 0x2b3e0000
	v_and_b32_e32 v6, 28, v1
	v_mov_b32_e32 v7, v2
	v_lshl_add_u64 v[24:25], v[4:5], 0, s[10:11]
	s_mov_b64 s[10:11], 0x33be0000
	v_lshl_add_u64 v[6:7], s[8:9], 0, v[6:7]
	s_mov_b64 s[8:9], 0xff8000
	v_lshl_add_u64 v[26:27], v[4:5], 0, s[10:11]
	v_lshl_add_u64 v[28:29], v[6:7], 0, s[8:9]
	s_load_dwordx4 s[8:11], s[6:7], 0x98
	s_nop 0
	s_load_dwordx2 s[6:7], s[6:7], 0xb0
	v_lshl_or_b32 v6, v3, 3, s78
	v_mov_b32_e32 v7, v2
	v_lshlrev_b64 v[6:7], 2, v[6:7]
	s_waitcnt lgkmcnt(0)
	v_lshl_add_u64 v[32:33], s[8:9], 0, v[6:7]
	s_mov_b64 s[8:9], 0x34ce0000
	v_lshl_add_u64 v[36:37], v[4:5], 0, s[8:9]
	s_mov_b64 s[8:9], 0x35de0000
	v_lshl_add_u64 v[38:39], v[4:5], 0, s[8:9]
	s_lshl_b64 s[8:9], s[78:79], 2
	s_add_u32 s6, s6, s8
	v_lshl_add_u64 v[34:35], s[10:11], 0, v[6:7]
	s_addc_u32 s7, s7, s9
	v_lshlrev_b32_e32 v6, 5, v3
	v_mov_b32_e32 v7, v2
	v_lshl_add_u64 v[40:41], s[6:7], 0, v[6:7]
	s_mov_b64 s[6:7], 0x36ee0000
	v_lshl_add_u64 v[42:43], v[4:5], 0, s[6:7]
	s_mov_b64 s[6:7], 0x37fe0000
	v_lshl_add_u64 v[44:45], v[4:5], 0, s[6:7]
	s_add_u32 s6, s12, s8
	s_addc_u32 s7, s13, s9
	s_mov_b64 s[14:15], 0x60e0000
	v_lshl_add_u64 v[46:47], s[6:7], 0, v[6:7]
	s_mov_b64 s[6:7], 0xa4e0000
	v_lshl_add_u64 v[30:31], v[4:5], 0, s[14:15]
	v_lshl_add_u64 v[48:49], v[4:5], 0, s[6:7]
	s_mov_b64 s[6:7], 0
	global_load_dwordx4 v[190:193], v[32:33], off offset:16
	global_load_dwordx4 v[194:197], v[32:33], off
	global_load_dwordx4 v[198:201], v[34:35], off offset:16
	global_load_dwordx4 v[202:205], v[34:35], off
	global_load_dwordx4 v[206:209], v[40:41], off offset:16
	global_load_dwordx4 v[210:213], v[40:41], off
	global_load_dwordx4 v[214:217], v[46:47], off
	global_load_dwordx4 v[218:221], v[46:47], off offset:16
.LBB0_743:
	v_mad_i64_i32 v[70:71], s[8:9], v0, s81, v[48:49]
	global_load_dwordx4 v[52:55], v[70:71], off
	global_load_dwordx4 v[60:63], v[70:71], off offset:1024
	v_ashrrev_i32_e32 v1, 31, v0
	v_lshlrev_b64 v[56:57], 10, v[0:1]
	v_lshl_add_u64 v[4:5], v[24:25], 0, v[56:57]
	global_load_dwordx4 v[12:15], v[4:5], off
	v_lshl_add_u64 v[4:5], v[26:27], 0, v[56:57]
	v_add_co_u32_e32 v20, vcc, s52, v70
	global_load_dwordx4 v[8:11], v[4:5], off
	v_lshl_add_u64 v[4:5], v[36:37], 0, v[56:57]
	v_lshl_add_u64 v[6:7], v[38:39], 0, v[56:57]
	v_addc_co_u32_e32 v21, vcc, 0, v71, vcc
	v_add_co_u32_e32 v226, vcc, s63, v70
	s_nop 1
	v_addc_co_u32_e32 v227, vcc, 0, v71, vcc
	global_load_dwordx4 v[16:19], v[4:5], off
	s_nop 0
	global_load_dwordx4 v[4:7], v[6:7], off
	v_lshlrev_b64 v[50:51], 5, v[0:1]
	global_load_dwordx4 v[20:23], v[20:21], off offset:3840
	v_lshl_add_u64 v[50:51], v[28:29], 0, v[50:51]
	global_load_dword v58, v[50:51], off
	v_lshl_add_u64 v[50:51], v[30:31], 0, v[56:57]
	v_lshl_add_u64 v[68:69], v[42:43], 0, v[56:57]
	v_lshl_add_u64 v[56:57], v[44:45], 0, v[56:57]
	global_load_dwordx4 v[84:87], v[68:69], off
	global_load_dwordx4 v[88:91], v[56:57], off
	global_load_dwordx4 v[222:225], v[226:227], off offset:2880
	s_brev_b32 s8, 60
	v_add_u32_e32 v0, s73, v0
	s_waitcnt vmcnt(10)
	v_lshlrev_b32_e32 v56, 16, v55
	v_and_b32_e32 v57, 0xffff0000, v55
	s_waitcnt vmcnt(9)
	v_lshlrev_b32_e32 v68, 16, v63
	v_and_b32_e32 v69, 0xffff0000, v63
	v_lshlrev_b32_e32 v92, 16, v54
	v_and_b32_e32 v93, 0xffff0000, v54
	v_lshlrev_b32_e32 v54, 16, v62
	v_and_b32_e32 v55, 0xffff0000, v62
	v_lshlrev_b32_e32 v62, 16, v53
	v_and_b32_e32 v63, 0xffff0000, v53
	v_lshlrev_b32_e32 v94, 16, v61
	v_and_b32_e32 v95, 0xffff0000, v61
	v_lshlrev_b32_e32 v96, 16, v52
	v_and_b32_e32 v97, 0xffff0000, v52
	v_lshlrev_b32_e32 v52, 16, v60
	v_and_b32_e32 v53, 0xffff0000, v60
	v_pk_add_f32 v[60:61], v[62:63], v[94:95]
	v_pk_add_f32 v[62:63], v[96:97], v[52:53]
	v_pk_add_f32 v[54:55], v[92:93], v[54:55]
	v_add_f32_e32 v1, 0, v62
	v_add_f32_e32 v1, v63, v1
	v_add_f32_e32 v1, v60, v1
	v_add_f32_e32 v1, v61, v1
	v_add_f32_e32 v1, v54, v1
	v_pk_add_f32 v[56:57], v[56:57], v[68:69]
	v_add_f32_e32 v1, v55, v1
	v_add_f32_e32 v1, v56, v1
	v_add_f32_e32 v1, v57, v1
	ds_bpermute_b32 v3, v170, v1
	s_waitcnt vmcnt(8)
	v_cvt_f32_f16_e32 v68, v15
	v_cvt_f32_f16_sdwa v69, v15 dst_sel:DWORD dst_unused:UNUSED_PAD src0_sel:WORD_1
	s_waitcnt vmcnt(7)
	v_cvt_f32_f16_e32 v92, v11
	v_cvt_f32_f16_sdwa v93, v11 dst_sel:DWORD dst_unused:UNUSED_PAD src0_sel:WORD_1
	s_waitcnt lgkmcnt(0)
	v_add_f32_e32 v1, v1, v3
	ds_bpermute_b32 v3, v171, v1
	v_cvt_f32_f16_e32 v94, v14
	v_cvt_f32_f16_sdwa v95, v14 dst_sel:DWORD dst_unused:UNUSED_PAD src0_sel:WORD_1
	v_cvt_f32_f16_e32 v14, v10
	v_cvt_f32_f16_sdwa v15, v10 dst_sel:DWORD dst_unused:UNUSED_PAD src0_sel:WORD_1
	s_waitcnt lgkmcnt(0)
	v_add_f32_e32 v1, v1, v3
	ds_bpermute_b32 v3, v172, v1
	v_cvt_f32_f16_e32 v10, v13
	v_cvt_f32_f16_sdwa v11, v13 dst_sel:DWORD dst_unused:UNUSED_PAD src0_sel:WORD_1
	v_cvt_f32_f16_e32 v96, v9
	v_cvt_f32_f16_sdwa v97, v9 dst_sel:DWORD dst_unused:UNUSED_PAD src0_sel:WORD_1
	s_waitcnt lgkmcnt(0)
; #define p (kparams())
; __device__ __forceinline__ void mixer_post(const int wv_, KPR p, int l) {
;     ...
; #pragma unroll
;       for (int e = 0; e < 8; ++e) { const int c = c0 + e; y[e] = (y[e] * rstd * p->in[I_RWLNW][l * C + c] + p->in[I_RWLNB][l * C + c] + rk * v[e]) * g[e]; }
;       st8(Y + (size_t)row * 512 + c0, y); }
; #pragma unroll
;     for (int mx = 0; mx < 2; ++mx) {
;       const bf16_t* O = mx == 0 ? OH : OG; const float* nw = (mx == 0 ? p->in[I_HGNORM] : p->in[I_GLANORM]) + l * C;
;       float a[8], bq[8], gt[8], y[8];
;       ld8(O + (size_t)row * 512 + c0, a); ld8(O + AE + (size_t)row * 512 + c0, bq); ld8(pr + (mx == 0 ? O_HG : O_GG) + c0, gt);
	v_add_f32_e32 v1, v1, v3
	v_mul_f32_e32 v102, 0x3c800000, v1
	v_pk_add_f32 v[62:63], v[62:63], v[102:103] op_sel_hi:[1,0] neg_lo:[0,1] neg_hi:[0,1]
	v_pk_add_f32 v[60:61], v[60:61], v[102:103] op_sel_hi:[1,0] neg_lo:[0,1] neg_hi:[0,1]
	v_pk_add_f32 v[104:105], v[54:55], v[102:103] op_sel_hi:[1,0] neg_lo:[0,1] neg_hi:[0,1]
	v_pk_mul_f32 v[54:55], v[62:63], v[62:63]
	v_pk_add_f32 v[102:103], v[56:57], v[102:103] op_sel_hi:[1,0] neg_lo:[0,1] neg_hi:[0,1]
	v_pk_mul_f32 v[56:57], v[60:61], v[60:61]
	v_add_f32_e32 v1, v54, v55
	v_add_f32_e32 v1, v56, v1
	v_pk_mul_f32 v[106:107], v[104:105], v[104:105]
	v_add_f32_e32 v1, v57, v1
	v_add_f32_e32 v1, v106, v1
	v_pk_mul_f32 v[108:109], v[102:103], v[102:103]
	v_add_f32_e32 v1, v107, v1
	v_add_f32_e32 v1, v108, v1
	v_add_f32_e32 v1, v109, v1
	ds_bpermute_b32 v3, v170, v1
	s_waitcnt vmcnt(4)
	v_lshlrev_b32_e32 v106, 16, v22
	v_cvt_f32_f16_e32 v98, v12
	v_cvt_f32_f16_sdwa v99, v12 dst_sel:DWORD dst_unused:UNUSED_PAD src0_sel:WORD_1
	v_cvt_f32_f16_e32 v12, v8
	s_waitcnt lgkmcnt(0)
	v_add_f32_e32 v1, v1, v3
	ds_bpermute_b32 v3, v171, v1
	v_cvt_f32_f16_sdwa v13, v8 dst_sel:DWORD dst_unused:UNUSED_PAD src0_sel:WORD_1
	v_lshlrev_b32_e32 v8, 16, v19
	v_and_b32_e32 v9, 0xffff0000, v19
	v_lshlrev_b32_e32 v56, 16, v18
	s_waitcnt lgkmcnt(0)
	v_add_f32_e32 v1, v1, v3
	ds_bpermute_b32 v3, v172, v1
	v_and_b32_e32 v57, 0xffff0000, v18
	v_lshlrev_b32_e32 v18, 16, v6
	v_and_b32_e32 v19, 0xffff0000, v6
	v_mul_f32_e32 v6, 0xbfb8aa3b, v106
	s_waitcnt lgkmcnt(0)
	v_add_f32_e32 v1, v1, v3
	v_fmamk_f32 v1, v1, 0x3c800000, v180
	v_mul_f32_e32 v3, 0x4b800000, v1
	v_cmp_gt_f32_e32 vcc, s96, v1
	v_exp_f32_e32 v6, v6
	v_and_b32_e32 v107, 0xffff0000, v22
	v_cndmask_b32_e32 v1, v1, v3, vcc
	v_rsq_f32_e32 v1, v1
	v_add_f32_e32 v6, 1.0, v6
	v_pk_add_f32 v[56:57], v[56:57], v[18:19]
	v_rcp_f32_e32 v18, v6
	v_mul_f32_e32 v6, 0x45800000, v1
	v_lshlrev_b32_e32 v100, 16, v7
	v_and_b32_e32 v101, 0xffff0000, v7
	v_mul_f32_e32 v7, 0xbfb8aa3b, v107
	v_cndmask_b32_e32 v6, v1, v6, vcc
	v_lshlrev_b32_e32 v52, 16, v23
	v_and_b32_e32 v53, 0xffff0000, v23
	v_pk_add_f32 v[54:55], v[8:9], v[100:101]
	v_exp_f32_e32 v3, v7
	v_pk_mul_f32 v[8:9], v[62:63], v[6:7] op_sel_hi:[1,0]
	v_pk_mul_f32 v[22:23], v[60:61], v[6:7] op_sel_hi:[1,0]
	v_pk_mul_f32 v[60:61], v[104:105], v[6:7] op_sel_hi:[1,0]
	v_pk_mul_f32 v[6:7], v[102:103], v[6:7] op_sel_hi:[1,0]
	s_waitcnt vmcnt(3)
	v_pk_fma_f32 v[8:9], v[194:195], v[8:9], v[202:203]
	v_pk_fma_f32 v[22:23], v[196:197], v[22:23], v[204:205]
	v_pk_fma_f32 v[60:61], v[190:191], v[60:61], v[198:199]
	v_pk_fma_f32 v[6:7], v[192:193], v[6:7], v[200:201]
	v_pk_fma_f32 v[8:9], v[58:59], v[98:99], v[8:9] op_sel_hi:[0,1,1]
	v_pk_fma_f32 v[10:11], v[58:59], v[10:11], v[22:23] op_sel_hi:[0,1,1]
	v_pk_fma_f32 v[22:23], v[58:59], v[94:95], v[60:61] op_sel_hi:[0,1,1]
	v_pk_fma_f32 v[6:7], v[58:59], v[68:69], v[6:7] op_sel_hi:[0,1,1]
	v_pk_mul_f32 v[8:9], v[8:9], v[12:13]
	v_pk_mul_f32 v[10:11], v[10:11], v[96:97]
	v_pk_mul_f32 v[12:13], v[22:23], v[14:15]
	v_pk_mul_f32 v[14:15], v[6:7], v[92:93]
	v_cvt_pk_bf16_f32 v6, v8, v9
	v_cvt_pk_bf16_f32 v7, v10, v11
	v_cvt_pk_bf16_f32 v8, v12, v13
	v_cvt_pk_bf16_f32 v9, v14, v15
	global_store_dwordx4 v[50:51], v[6:9], off
	v_add_f32_e32 v1, 1.0, v3
	v_rcp_f32_e32 v19, v1
	v_lshlrev_b32_e32 v22, 16, v5
	v_and_b32_e32 v23, 0xffff0000, v5
	v_lshlrev_b32_e32 v62, 16, v21
	v_pk_mul_f32 v[58:59], v[18:19], v[106:107]
	v_lshlrev_b32_e32 v18, 16, v17
	v_and_b32_e32 v19, 0xffff0000, v17
	v_pk_add_f32 v[60:61], v[18:19], v[22:23]
	v_lshlrev_b32_e32 v18, 16, v16
	v_and_b32_e32 v19, 0xffff0000, v16
	v_lshlrev_b32_e32 v16, 16, v4
	v_and_b32_e32 v17, 0xffff0000, v4
	v_and_b32_e32 v63, 0xffff0000, v21
	v_lshlrev_b32_e32 v68, 16, v20
	v_and_b32_e32 v69, 0xffff0000, v20
	v_pk_add_f32 v[66:67], v[18:19], v[16:17]
	s_waitcnt vmcnt(3)
	v_lshlrev_b32_e32 v18, 16, v86
	v_and_b32_e32 v19, 0xffff0000, v86
	s_waitcnt vmcnt(2)
	v_lshlrev_b32_e32 v20, 16, v90
	v_and_b32_e32 v21, 0xffff0000, v90
	v_pk_add_f32 v[18:19], v[18:19], v[20:21]
	v_lshlrev_b32_e32 v20, 16, v85
	v_and_b32_e32 v21, 0xffff0000, v85
	v_lshlrev_b32_e32 v22, 16, v89
	v_and_b32_e32 v23, 0xffff0000, v89
	v_pk_add_f32 v[20:21], v[20:21], v[22:23]
	v_lshlrev_b32_e32 v22, 16, v84
	v_and_b32_e32 v23, 0xffff0000, v84
	v_lshlrev_b32_e32 v78, 16, v88
	v_and_b32_e32 v79, 0xffff0000, v88
	v_pk_add_f32 v[22:23], v[22:23], v[78:79]
	v_mov_b32_e32 v81, v67
	v_mov_b32_e32 v80, v23
	v_pk_mul_f32 v[72:73], v[60:61], v[60:61]
	v_pk_mul_f32 v[76:77], v[20:21], v[20:21]
	v_mov_b32_e32 v78, v22
	v_mov_b32_e32 v79, v66
	v_pk_mul_f32 v[80:81], v[80:81], v[80:81]
	v_pk_mul_f32 v[6:7], v[56:57], v[56:57]
	v_pk_fma_f32 v[78:79], v[78:79], v[78:79], v[80:81]
	v_mov_b32_e32 v80, v76
	v_mov_b32_e32 v81, v72
	v_lshlrev_b32_e32 v4, 16, v87
	v_and_b32_e32 v5, 0xffff0000, v87
	v_lshlrev_b32_e32 v16, 16, v91
	v_and_b32_e32 v17, 0xffff0000, v91
	v_pk_mul_f32 v[74:75], v[18:19], v[18:19]
	v_pk_add_f32 v[78:79], v[80:81], v[78:79]
	v_mov_b32_e32 v72, v77
	v_pk_add_f32 v[16:17], v[4:5], v[16:17]
	v_pk_add_f32 v[72:73], v[72:73], v[78:79]
	v_mov_b32_e32 v76, v74
	v_mov_b32_e32 v77, v6
	v_pk_mul_f32 v[100:101], v[54:55], v[54:55]
	v_pk_mul_f32 v[4:5], v[16:17], v[16:17]
	v_pk_add_f32 v[72:73], v[76:77], v[72:73]
	v_mov_b32_e32 v6, v75
	v_pk_add_f32 v[6:7], v[6:7], v[72:73]
	v_mov_b32_e32 v72, v4
	v_mov_b32_e32 v73, v100
	v_pk_add_f32 v[6:7], v[72:73], v[6:7]
	v_mov_b32_e32 v100, v5
	v_pk_add_f32 v[4:5], v[100:101], v[6:7]
	ds_bpermute_b32 v7, v170, v5
	ds_bpermute_b32 v6, v170, v4
	v_mul_f32_e32 v1, 0xbfb8aa3b, v62
	v_exp_f32_e32 v1, v1
	v_mul_f32_e32 v3, 0xbfb8aa3b, v63
	v_exp_f32_e32 v3, v3
	s_waitcnt lgkmcnt(0)
; __device__ __forceinline__ float sigm(float x) { return __builtin_amdgcn_rcpf(1.f + __expf(-x)); }
; #define p (kparams())
; __device__ __forceinline__ void mixer_post(const int wv_, KPR p, int l) {
;     ...
;     for (int mx = 0; mx < 2; ++mx) {
;       const bf16_t* O = mx == 0 ? OH : OG; const float* nw = (mx == 0 ? p->in[I_HGNORM] : p->in[I_GLANORM]) + l * C;
;       float a[8], bq[8], gt[8], y[8];
;       ld8(O + (size_t)row * 512 + c0, a); ld8(O + AE + (size_t)row * 512 + c0, bq); ld8(pr + (mx == 0 ? O_HG : O_GG) + c0, gt);
;       float sq = 0.f;
; #pragma unroll
;       for (int e = 0; e < 8; ++e) { y[e] = a[e] + bq[e]; sq += y[e] * y[e]; }
;       const float rstd = rsqrtf(group_sum(sq, 16) * (1.f / 128.f) + 1e-6f);
; #pragma unroll
;       for (int e = 0; e < 8; ++e) y[e] = y[e] * rstd * nw[c0 + e] * (gt[e] * sigm(gt[e]));
;       st8(Y + (size_t)(1 + mx) * AE + (size_t)row * 512 + c0, y); }
	v_pk_add_f32 v[4:5], v[4:5], v[6:7]
	ds_bpermute_b32 v7, v171, v5
	ds_bpermute_b32 v6, v171, v4
	v_add_f32_e32 v1, 1.0, v1
	v_rcp_f32_e32 v64, v1
	v_add_f32_e32 v1, 1.0, v3
	v_rcp_f32_e32 v65, v1
	v_mul_f32_e32 v1, 0xbfb8aa3b, v68
	v_exp_f32_e32 v1, v1
	s_waitcnt lgkmcnt(0)
	v_pk_add_f32 v[74:75], v[4:5], v[6:7]
	v_add_f32_e32 v1, 1.0, v1
	v_rcp_f32_e32 v72, v1
	v_mul_f32_e32 v1, 0xbfb8aa3b, v69
	ds_bpermute_b32 v77, v172, v75
	ds_bpermute_b32 v76, v172, v74
	v_exp_f32_e32 v1, v1
	v_mul_f32_e32 v3, 0xbfb8aa3b, v53
	v_exp_f32_e32 v3, v3
	v_pk_mul_f32 v[62:63], v[64:65], v[62:63]
	v_add_f32_e32 v1, 1.0, v1
	s_waitcnt lgkmcnt(0)
	v_pk_add_f32 v[70:71], v[74:75], v[76:77]
	v_rcp_f32_e32 v73, v1
	v_mul_f32_e32 v1, 0xbfb8aa3b, v52
	ds_bpermute_b32 v77, v173, v71
	ds_bpermute_b32 v76, v173, v70
	v_exp_f32_e32 v1, v1
	v_pk_mul_f32 v[64:65], v[72:73], v[68:69]
	v_add_f32_e32 v1, 1.0, v1
	s_waitcnt lgkmcnt(0)
	v_pk_add_f32 v[70:71], v[70:71], v[76:77]
	v_rcp_f32_e32 v74, v1
	v_add_f32_e32 v1, 1.0, v3
	v_pk_fma_f32 v[70:71], v[70:71], s[8:9], v[152:153] op_sel_hi:[1,0,0]
	v_rcp_f32_e32 v75, v1
	v_mul_f32_e32 v1, 0x4b800000, v71
	v_cmp_gt_f32_e32 vcc, s96, v71
	v_pk_mul_f32 v[52:53], v[74:75], v[52:53]
	s_nop 0
	v_cndmask_b32_e32 v1, v71, v1, vcc
	v_rsq_f32_e32 v1, v1
	s_nop 0
	v_mul_f32_e32 v3, 0x45800000, v1
	v_cndmask_b32_e32 v68, v1, v3, vcc
	v_pk_mul_f32 v[56:57], v[56:57], v[68:69] op_sel_hi:[1,0]
	v_pk_mul_f32 v[66:67], v[66:67], v[68:69] op_sel_hi:[1,0]
	v_pk_mul_f32 v[8:9], v[206:207], v[56:57]
	v_pk_mul_f32 v[12:13], v[210:211], v[66:67]
	v_pk_mul_f32 v[60:61], v[60:61], v[68:69] op_sel_hi:[1,0]
	v_pk_mul_f32 v[56:57], v[58:59], v[8:9]
	v_pk_mul_f32 v[8:9], v[54:55], v[68:69] op_sel_hi:[1,0]
	v_pk_mul_f32 v[12:13], v[64:65], v[12:13]
	v_pk_mul_f32 v[14:15], v[212:213], v[60:61]
	v_pk_mul_f32 v[8:9], v[208:209], v[8:9]
	v_pk_mul_f32 v[14:15], v[62:63], v[14:15]
	v_pk_mul_f32 v[52:53], v[52:53], v[8:9]
	v_cvt_pk_bf16_f32 v8, v12, v13
	v_add_co_u32_e32 v12, vcc, s55, v50
	v_cvt_pk_bf16_f32 v9, v14, v15
	v_cvt_pk_bf16_f32 v10, v56, v57
	v_cvt_pk_bf16_f32 v11, v52, v53
	v_addc_co_u32_e32 v13, vcc, 0, v51, vcc
	global_store_dwordx4 v[12:13], v[8:11], off
	v_cmp_gt_f32_e32 vcc, s96, v70
	s_waitcnt vmcnt(2)
	v_lshlrev_b32_e32 v54, 16, v224
	v_and_b32_e32 v55, 0xffff0000, v224
	v_mul_f32_e32 v1, 0xbfb8aa3b, v54
	v_exp_f32_e32 v1, v1
	v_mul_f32_e32 v3, 0xbfb8aa3b, v55
	v_exp_f32_e32 v3, v3
	v_lshlrev_b32_e32 v56, 16, v223
	v_add_f32_e32 v1, 1.0, v1
	v_rcp_f32_e32 v6, v1
	v_add_f32_e32 v1, 1.0, v3
	v_mul_f32_e32 v3, 0xbfb8aa3b, v56
	v_and_b32_e32 v57, 0xffff0000, v223
	v_exp_f32_e32 v3, v3
	v_mul_f32_e32 v5, 0xbfb8aa3b, v57
	v_exp_f32_e32 v5, v5
	v_lshlrev_b32_e32 v60, 16, v222
	v_lshlrev_b32_e32 v52, 16, v225
	v_and_b32_e32 v53, 0xffff0000, v225
	v_rcp_f32_e32 v7, v1
	v_add_f32_e32 v1, 1.0, v3
	v_and_b32_e32 v61, 0xffff0000, v222
	v_mul_f32_e32 v3, 0xbfb8aa3b, v60
	v_exp_f32_e32 v3, v3
	v_mul_f32_e32 v4, 0xbfb8aa3b, v61
	v_rcp_f32_e32 v58, v1
	v_add_f32_e32 v1, 1.0, v5
	v_exp_f32_e32 v5, v4
	v_rcp_f32_e32 v59, v1
	v_add_f32_e32 v1, 1.0, v3
	v_rcp_f32_e32 v4, v1
	v_add_f32_e32 v1, 1.0, v5
	v_rcp_f32_e32 v5, v1
	v_mul_f32_e32 v1, 0x4b800000, v70
	v_cndmask_b32_e32 v1, v70, v1, vcc
	v_rsq_f32_e32 v1, v1
	v_pk_mul_f32 v[6:7], v[6:7], v[54:55]
	v_pk_mul_f32 v[54:55], v[58:59], v[56:57]
	v_pk_mul_f32 v[4:5], v[4:5], v[60:61]
	v_mul_f32_e32 v3, 0x45800000, v1
	v_cndmask_b32_e32 v56, v1, v3, vcc
	v_mul_f32_e32 v1, 0xbfb8aa3b, v52
	v_exp_f32_e32 v1, v1
	v_mul_f32_e32 v3, 0xbfb8aa3b, v53
	v_pk_mul_f32 v[22:23], v[22:23], v[56:57] op_sel_hi:[1,0]
	v_exp_f32_e32 v3, v3
	v_add_f32_e32 v1, 1.0, v1
	v_pk_mul_f32 v[8:9], v[214:215], v[22:23]
	s_nop 0
	v_pk_mul_f32 v[4:5], v[4:5], v[8:9]
	v_pk_mul_f32 v[8:9], v[20:21], v[56:57] op_sel_hi:[1,0]
	v_cvt_pk_bf16_f32 v4, v4, v5
	v_pk_mul_f32 v[8:9], v[216:217], v[8:9]
	v_pk_mul_f32 v[10:11], v[18:19], v[56:57] op_sel_hi:[1,0]
	v_pk_mul_f32 v[8:9], v[54:55], v[8:9]
	v_pk_mul_f32 v[10:11], v[218:219], v[10:11]
	v_rcp_f32_e32 v12, v1
	v_add_f32_e32 v1, 1.0, v3
	v_rcp_f32_e32 v13, v1
	v_pk_mul_f32 v[6:7], v[6:7], v[10:11]
	v_pk_mul_f32 v[10:11], v[16:17], v[56:57] op_sel_hi:[1,0]
	v_cvt_pk_bf16_f32 v5, v8, v9
	v_add_co_u32_e32 v8, vcc, 0x2200000, v50
	v_pk_mul_f32 v[10:11], v[220:221], v[10:11]
	v_pk_mul_f32 v[12:13], v[12:13], v[52:53]
	v_addc_co_u32_e32 v9, vcc, 0, v51, vcc
	v_pk_mul_f32 v[10:11], v[12:13], v[10:11]
	v_cmp_lt_i32_e32 vcc, s35, v0
	v_cvt_pk_bf16_f32 v6, v6, v7
	v_cvt_pk_bf16_f32 v7, v10, v11
	s_or_b64 s[6:7], vcc, s[6:7]
	global_store_dwordx4 v[8:9], v[4:7], off
	s_andn2_b64 exec, exec, s[6:7]
	s_cbranch_execnz .LBB0_743
